# v25 with the leading wave half's epilogue alignment barrier moved after the row-statistics phase and two row groups of the SwiGLU epilogue
# baseline (speedup 1.0000x reference)
; #define PG8_LAS __attribute__((address_space(3)))
; __device__ __forceinline__ unsigned cvt_pk_bf16(float lo, float hi) { unsigned r; asm volatile("v_cvt_pk_bf16_f32 %0, %1, %2" : "=v"(r) : "v"(lo), "v"(hi)); return r; }
; #define PG8_BAR __builtin_amdgcn_s_barrier()
; template <class Epi, class Sched, bool ALIGN_EPI = false, bool SP2 = false>
; __device__ __forceinline__ void gemm_phase(PG8_LAS unsigned char* lds, const Gemm g, const Sched& S, const Epi& E) {
;     ...
;         if constexpr (ALIGN_EPI) { if (wr == 0) PG8_BAR; }
;     __device__ __forceinline__ void operator()(const f32x4 (&acc)[2][2][4][2], const Unit& u, int wr, int wc, int fr, int fq, int ui) const {
;         const int row0 = u.pm * BM + wr * 64 + fr, col0 = u.pn * HALF + wc * 32 + 8 * fq;
;         const PG8_LAS unsigned long long* rs = (const PG8_LAS unsigned long long*)(spare + (ui & 1) * 2048) + wr * 64 + fr;
; #pragma unroll
;         for (int st = 0; st < 8; ++st) { const int ai = st >> 2, m = st & 3; const int row = row0 + ai * HALF + m * 16;
;             const float tot = (float)(rs[ai * HALF + m * 16] & 0xffffffffffffull) * (1.0f / 65536.0f);
;             const float rstd = 1.0f / sqrtf(tot * (1.0f / 1024.0f) + 1e-6f);
;             const float kq = -1.4426950408889634f * rstd, r2 = rstd * rstd;
;             unsigned wv[4];
; #pragma unroll
;             for (int h = 0; h < 4; ++h) { const int n = h >> 1, e = 2 * (h & 1);
;                 const f32x2 a2 = (f32x2){acc[ai][0][m][n][e], acc[ai][0][m][n][e + 1]}, b2 = (f32x2){acc[ai][1][m][n][e], acc[ai][1][m][n][e + 1]};
;                 const f32x2 t2 = a2 * kq; f32x2 d2; d2.x = __builtin_amdgcn_exp2f(t2.x); d2.y = __builtin_amdgcn_exp2f(t2.y); d2 = d2 + 1.0f;
;                 f32x2 q2; q2.x = __builtin_amdgcn_rcpf(d2.x); q2.y = __builtin_amdgcn_rcpf(d2.y);
;                 const f32x2 o2 = ((a2 * b2) * r2) * q2;
;                 wv[h] = cvt_pk_bf16(o2.x, o2.y); }
;             u32x4 w; w.x = wv[0]; w.y = wv[1]; w.z = wv[2]; w.w = wv[3];
;             *(u32x4*)(act + (size_t)row * 2816 + col0) = w; }
.Lpeel_exit_3:
.LBB0_570:
	s_lshl_b32 s0, s61, 11
	s_and_b32 s0, s0, 0x800
	v_add_u32_e32 v155, s0, v148
	ds_read_b64 v[160:161], v155
	ds_read_b64 v[162:163], v155 offset:128
	ds_read_b64 v[164:165], v155 offset:256
	ds_read_b64 v[166:167], v155 offset:384
	ds_read_b64 v[168:169], v155 offset:1024
	ds_read_b64 v[170:171], v155 offset:1152
	ds_read_b64 v[172:173], v155 offset:1280
	ds_read_b64 v[174:175], v155 offset:1408
	v_lshl_add_u32 v214, s44, 8, v146
	v_mov_b64_e32 v[216:217], s[38:39]
	v_lshl_or_b32 v218, s60, 7, v149
	v_ashrrev_i32_e32 v219, 31, v218
	v_mad_i64_i32 v[212:213], s[0:1], v214, s58, v[216:217]
	v_lshlrev_b64 v[218:219], 1, v[218:219]
	v_lshl_add_u64 v[212:213], v[212:213], 0, v[218:219]
	s_waitcnt lgkmcnt(0)
	v_and_b32_e32 v161, 0xffff, v161
	v_and_b32_e32 v163, 0xffff, v163
	v_and_b32_e32 v165, 0xffff, v165
	v_and_b32_e32 v167, 0xffff, v167
	v_and_b32_e32 v169, 0xffff, v169
	v_and_b32_e32 v171, 0xffff, v171
	v_and_b32_e32 v173, 0xffff, v173
	v_and_b32_e32 v175, 0xffff, v175
	v_cvt_f32_u32_e32 v160, v160
	v_cvt_f32_u32_e32 v162, v162
	v_cvt_f32_u32_e32 v164, v164
	v_cvt_f32_u32_e32 v166, v166
	v_cvt_f32_u32_e32 v168, v168
	v_cvt_f32_u32_e32 v170, v170
	v_cvt_f32_u32_e32 v172, v172
	v_cvt_f32_u32_e32 v174, v174
	v_cvt_f32_u32_e32 v161, v161
	v_cvt_f32_u32_e32 v163, v163
	v_cvt_f32_u32_e32 v165, v165
	v_cvt_f32_u32_e32 v167, v167
	v_cvt_f32_u32_e32 v169, v169
	v_cvt_f32_u32_e32 v171, v171
	v_cvt_f32_u32_e32 v173, v173
	v_cvt_f32_u32_e32 v175, v175
	v_fmamk_f32 v160, v161, 0x4f800000, v160
	v_fmamk_f32 v162, v163, 0x4f800000, v162
	v_fmamk_f32 v164, v165, 0x4f800000, v164
	v_fmamk_f32 v166, v167, 0x4f800000, v166
	v_fmamk_f32 v168, v169, 0x4f800000, v168
	v_fmamk_f32 v170, v171, 0x4f800000, v170
	v_fmamk_f32 v172, v173, 0x4f800000, v172
	v_fmamk_f32 v174, v175, 0x4f800000, v174
	v_fmamk_f32 v177, v160, 0x32800000, v153
	v_fmamk_f32 v179, v162, 0x32800000, v153
	v_fmamk_f32 v181, v164, 0x32800000, v153
	v_fmamk_f32 v183, v166, 0x32800000, v153
	v_fmamk_f32 v185, v168, 0x32800000, v153
	v_fmamk_f32 v187, v170, 0x32800000, v153
	v_fmamk_f32 v189, v172, 0x32800000, v153
	v_fmamk_f32 v191, v174, 0x32800000, v153
	v_rsq_f32_e32 v160, v177
	v_rsq_f32_e32 v162, v179
	v_rsq_f32_e32 v164, v181
	v_rsq_f32_e32 v166, v183
	v_rsq_f32_e32 v168, v185
	v_rsq_f32_e32 v170, v187
	v_rsq_f32_e32 v172, v189
	v_rsq_f32_e32 v174, v191
	v_mul_f32_e32 v161, v177, v160
	v_mul_f32_e32 v163, v179, v162
	v_mul_f32_e32 v165, v181, v164
	v_mul_f32_e32 v167, v183, v166
	v_mul_f32_e32 v169, v185, v168
	v_mul_f32_e32 v171, v187, v170
	v_mul_f32_e32 v173, v189, v172
	v_mul_f32_e32 v175, v191, v174
	v_fma_f32 v161, -v161, v160, 1.0
	v_fma_f32 v163, -v163, v162, 1.0
	v_fma_f32 v165, -v165, v164, 1.0
	v_fma_f32 v167, -v167, v166, 1.0
	v_fma_f32 v169, -v169, v168, 1.0
	v_fma_f32 v171, -v171, v170, 1.0
	v_fma_f32 v173, -v173, v172, 1.0
	v_fma_f32 v175, -v175, v174, 1.0
	v_mul_f32_e32 v176, 0.5, v160
	v_mul_f32_e32 v178, 0.5, v162
	v_mul_f32_e32 v180, 0.5, v164
	v_mul_f32_e32 v182, 0.5, v166
	v_mul_f32_e32 v184, 0.5, v168
	v_mul_f32_e32 v186, 0.5, v170
	v_mul_f32_e32 v188, 0.5, v172
	v_mul_f32_e32 v190, 0.5, v174
	v_fmac_f32_e32 v160, v161, v176
	v_fmac_f32_e32 v162, v163, v178
	v_fmac_f32_e32 v164, v165, v180
	v_fmac_f32_e32 v166, v167, v182
	v_fmac_f32_e32 v168, v169, v184
	v_fmac_f32_e32 v170, v171, v186
	v_fmac_f32_e32 v172, v173, v188
	v_fmac_f32_e32 v174, v175, v190
	v_mul_f32_e32 v176, 0xbfb8aa3b, v160
	v_mul_f32_e32 v178, 0xbfb8aa3b, v162
	v_mul_f32_e32 v180, 0xbfb8aa3b, v164
	v_mul_f32_e32 v182, 0xbfb8aa3b, v166
	v_mul_f32_e32 v184, 0xbfb8aa3b, v168
	v_mul_f32_e32 v186, 0xbfb8aa3b, v170
	v_mul_f32_e32 v188, 0xbfb8aa3b, v172
	v_mul_f32_e32 v190, 0xbfb8aa3b, v174
	v_pk_mul_f32 v[192:193], v[124:125], v[176:177] op_sel_hi:[1,0]
	v_pk_mul_f32 v[194:195], v[126:127], v[176:177] op_sel_hi:[1,0]
	v_pk_mul_f32 v[196:197], v[116:117], v[176:177] op_sel_hi:[1,0]
	v_pk_mul_f32 v[198:199], v[118:119], v[176:177] op_sel_hi:[1,0]
	v_exp_f32_e32 v192, v192
	v_exp_f32_e32 v193, v193
	v_exp_f32_e32 v194, v194
	v_exp_f32_e32 v195, v195
	v_exp_f32_e32 v196, v196
	v_exp_f32_e32 v197, v197
	v_exp_f32_e32 v198, v198
	v_exp_f32_e32 v199, v199
	v_pk_mul_f32 v[120:121], v[124:125], v[120:121]
	v_pk_mul_f32 v[122:123], v[126:127], v[122:123]
	v_pk_mul_f32 v[112:113], v[116:117], v[112:113]
	v_pk_mul_f32 v[114:115], v[118:119], v[114:115]
	v_pk_fma_f32 v[192:193], v[192:193], v[176:177], v[176:177] op_sel:[0,1,1] op_sel_hi:[1,1,1]
	v_pk_fma_f32 v[194:195], v[194:195], v[176:177], v[176:177] op_sel:[0,1,1] op_sel_hi:[1,1,1]
	v_pk_fma_f32 v[196:197], v[196:197], v[176:177], v[176:177] op_sel:[0,1,1] op_sel_hi:[1,1,1]
	v_pk_fma_f32 v[198:199], v[198:199], v[176:177], v[176:177] op_sel:[0,1,1] op_sel_hi:[1,1,1]
	s_mov_b64 s[0:1], 0x16000
	v_rcp_f32_e32 v192, v192
	v_rcp_f32_e32 v193, v193
	v_rcp_f32_e32 v194, v194
	v_rcp_f32_e32 v195, v195
	v_rcp_f32_e32 v196, v196
	v_rcp_f32_e32 v197, v197
	v_rcp_f32_e32 v198, v198
	v_rcp_f32_e32 v199, v199
	v_pk_mul_f32 v[120:121], v[120:121], v[192:193]
	v_pk_mul_f32 v[122:123], v[122:123], v[194:195]
	v_pk_mul_f32 v[112:113], v[112:113], v[196:197]
	v_pk_mul_f32 v[114:115], v[114:115], v[198:199]
	v_cvt_pk_bf16_f32 v200, v120, v121
	v_cvt_pk_bf16_f32 v201, v122, v123
	v_cvt_pk_bf16_f32 v202, v112, v113
	v_cvt_pk_bf16_f32 v203, v114, v115
	global_store_dwordx4 v[212:213], v[200:203], off sc1
	v_pk_mul_f32 v[192:193], v[108:109], v[178:179] op_sel_hi:[1,0]
	v_pk_mul_f32 v[194:195], v[110:111], v[178:179] op_sel_hi:[1,0]
	v_pk_mul_f32 v[196:197], v[100:101], v[178:179] op_sel_hi:[1,0]
	v_pk_mul_f32 v[198:199], v[102:103], v[178:179] op_sel_hi:[1,0]
; __device__ __forceinline__ unsigned cvt_pk_bf16(float lo, float hi) { unsigned r; asm volatile("v_cvt_pk_bf16_f32 %0, %1, %2" : "=v"(r) : "v"(lo), "v"(hi)); return r; }
; #define PG8_BAR __builtin_amdgcn_s_barrier()
; template <class Epi, class Sched, bool ALIGN_EPI = false, bool SP2 = false>
; __device__ __forceinline__ void gemm_phase(PG8_LAS unsigned char* lds, const Gemm g, const Sched& S, const Epi& E) {
;     ...
;         if constexpr (ALIGN_EPI) { if (wr == 0) PG8_BAR; }
;     __device__ __forceinline__ void operator()(const f32x4 (&acc)[2][2][4][2], const Unit& u, int wr, int wc, int fr, int fq, int ui) const {
;     ...
;         for (int st = 0; st < 8; ++st) { const int ai = st >> 2, m = st & 3; const int row = row0 + ai * HALF + m * 16;
;             const float tot = (float)(rs[ai * HALF + m * 16] & 0xffffffffffffull) * (1.0f / 65536.0f);
;             const float rstd = 1.0f / sqrtf(tot * (1.0f / 1024.0f) + 1e-6f);
;             const float kq = -1.4426950408889634f * rstd, r2 = rstd * rstd;
;             unsigned wv[4];
; #pragma unroll
;             for (int h = 0; h < 4; ++h) { const int n = h >> 1, e = 2 * (h & 1);
;                 const f32x2 a2 = (f32x2){acc[ai][0][m][n][e], acc[ai][0][m][n][e + 1]}, b2 = (f32x2){acc[ai][1][m][n][e], acc[ai][1][m][n][e + 1]};
;                 const f32x2 t2 = a2 * kq; f32x2 d2; d2.x = __builtin_amdgcn_exp2f(t2.x); d2.y = __builtin_amdgcn_exp2f(t2.y); d2 = d2 + 1.0f;
;                 f32x2 q2; q2.x = __builtin_amdgcn_rcpf(d2.x); q2.y = __builtin_amdgcn_rcpf(d2.y);
;                 const f32x2 o2 = ((a2 * b2) * r2) * q2;
;                 wv[h] = cvt_pk_bf16(o2.x, o2.y); }
;             u32x4 w; w.x = wv[0]; w.y = wv[1]; w.z = wv[2]; w.w = wv[3];
;             *(u32x4*)(act + (size_t)row * 2816 + col0) = w; }
	v_exp_f32_e32 v192, v192
	v_exp_f32_e32 v193, v193
	v_exp_f32_e32 v194, v194
	v_exp_f32_e32 v195, v195
	v_exp_f32_e32 v196, v196
	v_exp_f32_e32 v197, v197
	v_exp_f32_e32 v198, v198
	v_exp_f32_e32 v199, v199
	v_pk_mul_f32 v[104:105], v[108:109], v[104:105]
	v_pk_mul_f32 v[106:107], v[110:111], v[106:107]
	v_pk_mul_f32 v[96:97], v[100:101], v[96:97]
	v_pk_mul_f32 v[98:99], v[102:103], v[98:99]
	v_pk_fma_f32 v[192:193], v[192:193], v[178:179], v[178:179] op_sel:[0,1,1] op_sel_hi:[1,1,1]
	v_pk_fma_f32 v[194:195], v[194:195], v[178:179], v[178:179] op_sel:[0,1,1] op_sel_hi:[1,1,1]
	v_pk_fma_f32 v[196:197], v[196:197], v[178:179], v[178:179] op_sel:[0,1,1] op_sel_hi:[1,1,1]
	v_pk_fma_f32 v[198:199], v[198:199], v[178:179], v[178:179] op_sel:[0,1,1] op_sel_hi:[1,1,1]
	v_lshl_add_u64 v[212:213], v[212:213], 0, s[0:1]
	v_rcp_f32_e32 v192, v192
	v_rcp_f32_e32 v193, v193
	v_rcp_f32_e32 v194, v194
	v_rcp_f32_e32 v195, v195
	v_rcp_f32_e32 v196, v196
	v_rcp_f32_e32 v197, v197
	v_rcp_f32_e32 v198, v198
	v_rcp_f32_e32 v199, v199
	v_pk_mul_f32 v[104:105], v[104:105], v[192:193]
	v_pk_mul_f32 v[106:107], v[106:107], v[194:195]
	v_pk_mul_f32 v[96:97], v[96:97], v[196:197]
	v_pk_mul_f32 v[98:99], v[98:99], v[198:199]
	v_cvt_pk_bf16_f32 v208, v104, v105
	v_cvt_pk_bf16_f32 v209, v106, v107
	v_cvt_pk_bf16_f32 v210, v96, v97
	v_cvt_pk_bf16_f32 v211, v98, v99
	global_store_dwordx4 v[212:213], v[208:211], off sc1
	s_and_b64 vcc, exec, s[10:11]
	s_cbranch_vccz .Lp5_epi_nobar
	s_barrier
.Lp5_epi_nobar:
	v_pk_mul_f32 v[192:193], v[92:93], v[180:181] op_sel_hi:[1,0]
	v_pk_mul_f32 v[194:195], v[94:95], v[180:181] op_sel_hi:[1,0]
	v_pk_mul_f32 v[196:197], v[84:85], v[180:181] op_sel_hi:[1,0]
	v_pk_mul_f32 v[198:199], v[86:87], v[180:181] op_sel_hi:[1,0]
	v_exp_f32_e32 v192, v192
	v_exp_f32_e32 v193, v193
	v_exp_f32_e32 v194, v194
	v_exp_f32_e32 v195, v195
	v_exp_f32_e32 v196, v196
	v_exp_f32_e32 v197, v197
	v_exp_f32_e32 v198, v198
	v_exp_f32_e32 v199, v199
	v_pk_mul_f32 v[88:89], v[92:93], v[88:89]
	v_pk_mul_f32 v[90:91], v[94:95], v[90:91]
	v_pk_mul_f32 v[80:81], v[84:85], v[80:81]
	v_pk_mul_f32 v[82:83], v[86:87], v[82:83]
	v_pk_fma_f32 v[192:193], v[192:193], v[180:181], v[180:181] op_sel:[0,1,1] op_sel_hi:[1,1,1]
	v_pk_fma_f32 v[194:195], v[194:195], v[180:181], v[180:181] op_sel:[0,1,1] op_sel_hi:[1,1,1]
	v_pk_fma_f32 v[196:197], v[196:197], v[180:181], v[180:181] op_sel:[0,1,1] op_sel_hi:[1,1,1]
	v_pk_fma_f32 v[198:199], v[198:199], v[180:181], v[180:181] op_sel:[0,1,1] op_sel_hi:[1,1,1]
	v_lshl_add_u64 v[212:213], v[212:213], 0, s[0:1]
	v_rcp_f32_e32 v192, v192
	v_rcp_f32_e32 v193, v193
	v_rcp_f32_e32 v194, v194
	v_rcp_f32_e32 v195, v195
	v_rcp_f32_e32 v196, v196
	v_rcp_f32_e32 v197, v197
	v_rcp_f32_e32 v198, v198
	v_rcp_f32_e32 v199, v199
	v_pk_mul_f32 v[88:89], v[88:89], v[192:193]
	v_pk_mul_f32 v[90:91], v[90:91], v[194:195]
	v_pk_mul_f32 v[80:81], v[80:81], v[196:197]
	v_pk_mul_f32 v[82:83], v[82:83], v[198:199]
	v_cvt_pk_bf16_f32 v200, v88, v89
	v_cvt_pk_bf16_f32 v201, v90, v91
	v_cvt_pk_bf16_f32 v202, v80, v81
	v_cvt_pk_bf16_f32 v203, v82, v83
	global_store_dwordx4 v[212:213], v[200:203], off sc1
	v_pk_mul_f32 v[192:193], v[76:77], v[182:183] op_sel_hi:[1,0]
	v_pk_mul_f32 v[194:195], v[78:79], v[182:183] op_sel_hi:[1,0]
	v_pk_mul_f32 v[196:197], v[68:69], v[182:183] op_sel_hi:[1,0]
	v_pk_mul_f32 v[198:199], v[70:71], v[182:183] op_sel_hi:[1,0]
	v_exp_f32_e32 v192, v192
	v_exp_f32_e32 v193, v193
	v_exp_f32_e32 v194, v194
	v_exp_f32_e32 v195, v195
	v_exp_f32_e32 v196, v196
	v_exp_f32_e32 v197, v197
	v_exp_f32_e32 v198, v198
	v_exp_f32_e32 v199, v199
	v_pk_mul_f32 v[72:73], v[76:77], v[72:73]
	v_pk_mul_f32 v[74:75], v[78:79], v[74:75]
	v_pk_mul_f32 v[64:65], v[68:69], v[64:65]
	v_pk_mul_f32 v[66:67], v[70:71], v[66:67]
	v_pk_fma_f32 v[192:193], v[192:193], v[182:183], v[182:183] op_sel:[0,1,1] op_sel_hi:[1,1,1]
	v_pk_fma_f32 v[194:195], v[194:195], v[182:183], v[182:183] op_sel:[0,1,1] op_sel_hi:[1,1,1]
	v_pk_fma_f32 v[196:197], v[196:197], v[182:183], v[182:183] op_sel:[0,1,1] op_sel_hi:[1,1,1]
	v_pk_fma_f32 v[198:199], v[198:199], v[182:183], v[182:183] op_sel:[0,1,1] op_sel_hi:[1,1,1]
	v_lshl_add_u64 v[212:213], v[212:213], 0, s[0:1]
	v_rcp_f32_e32 v192, v192
	v_rcp_f32_e32 v193, v193
	v_rcp_f32_e32 v194, v194
	v_rcp_f32_e32 v195, v195
	v_rcp_f32_e32 v196, v196
	v_rcp_f32_e32 v197, v197
	v_rcp_f32_e32 v198, v198
	v_rcp_f32_e32 v199, v199
	v_pk_mul_f32 v[72:73], v[72:73], v[192:193]
	v_pk_mul_f32 v[74:75], v[74:75], v[194:195]
	v_pk_mul_f32 v[64:65], v[64:65], v[196:197]
	v_pk_mul_f32 v[66:67], v[66:67], v[198:199]
	v_cvt_pk_bf16_f32 v208, v72, v73
	v_cvt_pk_bf16_f32 v209, v74, v75
	v_cvt_pk_bf16_f32 v210, v64, v65
	v_cvt_pk_bf16_f32 v211, v66, v67
	global_store_dwordx4 v[212:213], v[208:211], off sc1
	v_pk_mul_f32 v[192:193], v[60:61], v[184:185] op_sel_hi:[1,0]
	v_pk_mul_f32 v[194:195], v[62:63], v[184:185] op_sel_hi:[1,0]
	v_pk_mul_f32 v[196:197], v[52:53], v[184:185] op_sel_hi:[1,0]
	v_pk_mul_f32 v[198:199], v[54:55], v[184:185] op_sel_hi:[1,0]
	v_exp_f32_e32 v192, v192
	v_exp_f32_e32 v193, v193
	v_exp_f32_e32 v194, v194
	v_exp_f32_e32 v195, v195
	v_exp_f32_e32 v196, v196
	v_exp_f32_e32 v197, v197
	v_exp_f32_e32 v198, v198
	v_exp_f32_e32 v199, v199
	v_pk_mul_f32 v[56:57], v[60:61], v[56:57]
	v_pk_mul_f32 v[58:59], v[62:63], v[58:59]
	v_pk_mul_f32 v[48:49], v[52:53], v[48:49]
	v_pk_mul_f32 v[50:51], v[54:55], v[50:51]
	v_pk_fma_f32 v[192:193], v[192:193], v[184:185], v[184:185] op_sel:[0,1,1] op_sel_hi:[1,1,1]
	v_pk_fma_f32 v[194:195], v[194:195], v[184:185], v[184:185] op_sel:[0,1,1] op_sel_hi:[1,1,1]
; __device__ __forceinline__ unsigned cvt_pk_bf16(float lo, float hi) { unsigned r; asm volatile("v_cvt_pk_bf16_f32 %0, %1, %2" : "=v"(r) : "v"(lo), "v"(hi)); return r; }
; #define PG8_BAR __builtin_amdgcn_s_barrier()
; template <class Epi, class Sched, bool ALIGN_EPI = false, bool SP2 = false>
; __device__ __forceinline__ void gemm_phase(PG8_LAS unsigned char* lds, const Gemm g, const Sched& S, const Epi& E) {
;     ...
;         cur = nxt; cA = nA; cB = nB; ++ui;
;         if constexpr (epi_prefetches<Epi>::value) E.prefetch(cur, ui, wid);
;         if constexpr (ALIGN_EPI) { if (wr == 1) PG8_BAR; }
;     __device__ __forceinline__ void operator()(const f32x4 (&acc)[2][2][4][2], const Unit& u, int wr, int wc, int fr, int fq, int ui) const {
;     ...
;         for (int st = 0; st < 8; ++st) { const int ai = st >> 2, m = st & 3; const int row = row0 + ai * HALF + m * 16;
;             const float tot = (float)(rs[ai * HALF + m * 16] & 0xffffffffffffull) * (1.0f / 65536.0f);
;             const float rstd = 1.0f / sqrtf(tot * (1.0f / 1024.0f) + 1e-6f);
;             const float kq = -1.4426950408889634f * rstd, r2 = rstd * rstd;
;             unsigned wv[4];
; #pragma unroll
;             for (int h = 0; h < 4; ++h) { const int n = h >> 1, e = 2 * (h & 1);
;                 const f32x2 a2 = (f32x2){acc[ai][0][m][n][e], acc[ai][0][m][n][e + 1]}, b2 = (f32x2){acc[ai][1][m][n][e], acc[ai][1][m][n][e + 1]};
;                 const f32x2 t2 = a2 * kq; f32x2 d2; d2.x = __builtin_amdgcn_exp2f(t2.x); d2.y = __builtin_amdgcn_exp2f(t2.y); d2 = d2 + 1.0f;
;                 f32x2 q2; q2.x = __builtin_amdgcn_rcpf(d2.x); q2.y = __builtin_amdgcn_rcpf(d2.y);
;                 const f32x2 o2 = ((a2 * b2) * r2) * q2;
;                 wv[h] = cvt_pk_bf16(o2.x, o2.y); }
;             u32x4 w; w.x = wv[0]; w.y = wv[1]; w.z = wv[2]; w.w = wv[3];
;             *(u32x4*)(act + (size_t)row * 2816 + col0) = w; }
	v_pk_fma_f32 v[196:197], v[196:197], v[184:185], v[184:185] op_sel:[0,1,1] op_sel_hi:[1,1,1]
	v_pk_fma_f32 v[198:199], v[198:199], v[184:185], v[184:185] op_sel:[0,1,1] op_sel_hi:[1,1,1]
	s_mov_b64 s[0:1], 0x6e000
	v_lshl_add_u64 v[212:213], v[212:213], 0, s[0:1]
	s_mov_b64 s[0:1], 0x16000
	v_rcp_f32_e32 v192, v192
	v_rcp_f32_e32 v193, v193
	v_rcp_f32_e32 v194, v194
	v_rcp_f32_e32 v195, v195
	v_rcp_f32_e32 v196, v196
	v_rcp_f32_e32 v197, v197
	v_rcp_f32_e32 v198, v198
	v_rcp_f32_e32 v199, v199
	v_pk_mul_f32 v[56:57], v[56:57], v[192:193]
	v_pk_mul_f32 v[58:59], v[58:59], v[194:195]
	v_pk_mul_f32 v[48:49], v[48:49], v[196:197]
	v_pk_mul_f32 v[50:51], v[50:51], v[198:199]
	v_cvt_pk_bf16_f32 v200, v56, v57
	v_cvt_pk_bf16_f32 v201, v58, v59
	v_cvt_pk_bf16_f32 v202, v48, v49
	v_cvt_pk_bf16_f32 v203, v50, v51
	global_store_dwordx4 v[212:213], v[200:203], off sc1
	v_pk_mul_f32 v[192:193], v[44:45], v[186:187] op_sel_hi:[1,0]
	v_pk_mul_f32 v[194:195], v[46:47], v[186:187] op_sel_hi:[1,0]
	v_pk_mul_f32 v[196:197], v[36:37], v[186:187] op_sel_hi:[1,0]
	v_pk_mul_f32 v[198:199], v[38:39], v[186:187] op_sel_hi:[1,0]
	v_exp_f32_e32 v192, v192
	v_exp_f32_e32 v193, v193
	v_exp_f32_e32 v194, v194
	v_exp_f32_e32 v195, v195
	v_exp_f32_e32 v196, v196
	v_exp_f32_e32 v197, v197
	v_exp_f32_e32 v198, v198
	v_exp_f32_e32 v199, v199
	v_pk_mul_f32 v[40:41], v[44:45], v[40:41]
	v_pk_mul_f32 v[42:43], v[46:47], v[42:43]
	v_pk_mul_f32 v[32:33], v[36:37], v[32:33]
	v_pk_mul_f32 v[34:35], v[38:39], v[34:35]
	v_pk_fma_f32 v[192:193], v[192:193], v[186:187], v[186:187] op_sel:[0,1,1] op_sel_hi:[1,1,1]
	v_pk_fma_f32 v[194:195], v[194:195], v[186:187], v[186:187] op_sel:[0,1,1] op_sel_hi:[1,1,1]
	v_pk_fma_f32 v[196:197], v[196:197], v[186:187], v[186:187] op_sel:[0,1,1] op_sel_hi:[1,1,1]
	v_pk_fma_f32 v[198:199], v[198:199], v[186:187], v[186:187] op_sel:[0,1,1] op_sel_hi:[1,1,1]
	v_lshl_add_u64 v[212:213], v[212:213], 0, s[0:1]
	v_rcp_f32_e32 v192, v192
	v_rcp_f32_e32 v193, v193
	v_rcp_f32_e32 v194, v194
	v_rcp_f32_e32 v195, v195
	v_rcp_f32_e32 v196, v196
	v_rcp_f32_e32 v197, v197
	v_rcp_f32_e32 v198, v198
	v_rcp_f32_e32 v199, v199
	v_pk_mul_f32 v[40:41], v[40:41], v[192:193]
	v_pk_mul_f32 v[42:43], v[42:43], v[194:195]
	v_pk_mul_f32 v[32:33], v[32:33], v[196:197]
	v_pk_mul_f32 v[34:35], v[34:35], v[198:199]
	v_cvt_pk_bf16_f32 v208, v40, v41
	v_cvt_pk_bf16_f32 v209, v42, v43
	v_cvt_pk_bf16_f32 v210, v32, v33
	v_cvt_pk_bf16_f32 v211, v34, v35
	global_store_dwordx4 v[212:213], v[208:211], off sc1
	v_pk_mul_f32 v[192:193], v[28:29], v[188:189] op_sel_hi:[1,0]
	v_pk_mul_f32 v[194:195], v[30:31], v[188:189] op_sel_hi:[1,0]
	v_pk_mul_f32 v[196:197], v[20:21], v[188:189] op_sel_hi:[1,0]
	v_pk_mul_f32 v[198:199], v[22:23], v[188:189] op_sel_hi:[1,0]
	v_exp_f32_e32 v192, v192
	v_exp_f32_e32 v193, v193
	v_exp_f32_e32 v194, v194
	v_exp_f32_e32 v195, v195
	v_exp_f32_e32 v196, v196
	v_exp_f32_e32 v197, v197
	v_exp_f32_e32 v198, v198
	v_exp_f32_e32 v199, v199
	v_pk_mul_f32 v[24:25], v[28:29], v[24:25]
	v_pk_mul_f32 v[26:27], v[30:31], v[26:27]
	v_pk_mul_f32 v[16:17], v[20:21], v[16:17]
	v_pk_mul_f32 v[18:19], v[22:23], v[18:19]
	v_pk_fma_f32 v[192:193], v[192:193], v[188:189], v[188:189] op_sel:[0,1,1] op_sel_hi:[1,1,1]
	v_pk_fma_f32 v[194:195], v[194:195], v[188:189], v[188:189] op_sel:[0,1,1] op_sel_hi:[1,1,1]
	v_pk_fma_f32 v[196:197], v[196:197], v[188:189], v[188:189] op_sel:[0,1,1] op_sel_hi:[1,1,1]
	v_pk_fma_f32 v[198:199], v[198:199], v[188:189], v[188:189] op_sel:[0,1,1] op_sel_hi:[1,1,1]
	v_lshl_add_u64 v[212:213], v[212:213], 0, s[0:1]
	v_rcp_f32_e32 v192, v192
	v_rcp_f32_e32 v193, v193
	v_rcp_f32_e32 v194, v194
	v_rcp_f32_e32 v195, v195
	v_rcp_f32_e32 v196, v196
	v_rcp_f32_e32 v197, v197
	v_rcp_f32_e32 v198, v198
	v_rcp_f32_e32 v199, v199
	v_pk_mul_f32 v[24:25], v[24:25], v[192:193]
	v_pk_mul_f32 v[26:27], v[26:27], v[194:195]
	v_pk_mul_f32 v[16:17], v[16:17], v[196:197]
	v_pk_mul_f32 v[18:19], v[18:19], v[198:199]
	v_cvt_pk_bf16_f32 v200, v24, v25
	v_cvt_pk_bf16_f32 v201, v26, v27
	v_cvt_pk_bf16_f32 v202, v16, v17
	v_cvt_pk_bf16_f32 v203, v18, v19
	global_store_dwordx4 v[212:213], v[200:203], off sc1
	v_pk_mul_f32 v[192:193], v[12:13], v[190:191] op_sel_hi:[1,0]
	v_pk_mul_f32 v[194:195], v[14:15], v[190:191] op_sel_hi:[1,0]
	v_pk_mul_f32 v[196:197], v[4:5], v[190:191] op_sel_hi:[1,0]
	v_pk_mul_f32 v[198:199], v[6:7], v[190:191] op_sel_hi:[1,0]
	v_exp_f32_e32 v192, v192
	v_exp_f32_e32 v193, v193
	v_exp_f32_e32 v194, v194
	v_exp_f32_e32 v195, v195
	v_exp_f32_e32 v196, v196
	v_exp_f32_e32 v197, v197
	v_exp_f32_e32 v198, v198
	v_exp_f32_e32 v199, v199
	v_pk_mul_f32 v[8:9], v[12:13], v[8:9]
	v_pk_mul_f32 v[10:11], v[14:15], v[10:11]
	v_pk_mul_f32 v[0:1], v[4:5], v[0:1]
	v_pk_mul_f32 v[2:3], v[6:7], v[2:3]
	v_pk_fma_f32 v[192:193], v[192:193], v[190:191], v[190:191] op_sel:[0,1,1] op_sel_hi:[1,1,1]
	v_pk_fma_f32 v[194:195], v[194:195], v[190:191], v[190:191] op_sel:[0,1,1] op_sel_hi:[1,1,1]
	v_pk_fma_f32 v[196:197], v[196:197], v[190:191], v[190:191] op_sel:[0,1,1] op_sel_hi:[1,1,1]
	v_pk_fma_f32 v[198:199], v[198:199], v[190:191], v[190:191] op_sel:[0,1,1] op_sel_hi:[1,1,1]
	v_lshl_add_u64 v[212:213], v[212:213], 0, s[0:1]
	v_rcp_f32_e32 v192, v192
	v_rcp_f32_e32 v193, v193
	v_rcp_f32_e32 v194, v194
	v_rcp_f32_e32 v195, v195
	v_rcp_f32_e32 v196, v196
	v_rcp_f32_e32 v197, v197
	v_rcp_f32_e32 v198, v198
	v_rcp_f32_e32 v199, v199
	v_pk_mul_f32 v[8:9], v[8:9], v[192:193]
	v_pk_mul_f32 v[10:11], v[10:11], v[194:195]
	v_pk_mul_f32 v[0:1], v[0:1], v[196:197]
	v_pk_mul_f32 v[2:3], v[2:3], v[198:199]
	v_cvt_pk_bf16_f32 v208, v8, v9
	v_cvt_pk_bf16_f32 v209, v10, v11
	v_cvt_pk_bf16_f32 v210, v0, v1
	v_cvt_pk_bf16_f32 v211, v2, v3
	global_store_dwordx4 v[212:213], v[208:211], off sc1
	s_andn2_b64 vcc, exec, s[2:3]
	s_mov_b64 s[0:1], -1
	s_cbranch_vccnz .LBB0_563
	s_lshl_b64 s[0:1], s[16:17], 11
	v_lshl_add_u64 v[0:1], v[136:137], 0, s[0:1]
	s_lshl_b32 s0, s59, 11
	s_and_b32 s0, s0, 0x800
	s_add_i32 m0, s23, s0
	s_andn2_b64 vcc, exec, s[6:7]
	global_load_lds_dword v[0:1], off
	s_cbranch_vccnz .LBB0_562
	s_barrier
	s_branch .LBB0_562
